# barrier 0: cooperative grid.sync replaced by the kernel's own counter barrier (second counter word zeroed by WG0 at start, launch flag checked before arrival, flag cleared at end)
# speedup vs baseline: 1.0075x; 1.0075x over previous
; #define LAS __attribute__((address_space(3)))
; __global__ void __launch_bounds__(512, 2) fwd_mega(Params p) {
;   extern __shared__ __attribute__((aligned(16))) unsigned char lds[];
;   cg::grid_group grid = cg::this_grid();
;   const int bid = blockIdx.x, nb = gridDim.x;
;   unsigned char* ws = p.ws;
;   LAS unsigned char* gl = (LAS unsigned char*)lds;
;   float* ss = (float*)(ws + OFF_SS);
;   unsigned* bar = (unsigned*)(ws + OFF_BAR);
;     ...
;   if (bid == 0 && threadIdx.x == 0) __hip_atomic_store(bar, 0u, __ATOMIC_RELAXED, __HIP_MEMORY_SCOPE_AGENT);
_Z8fwd_mega6Params:
	s_load_dwordx4 s[4:7], s[0:1], 0x80
	s_load_dwordx16 s[8:23], s[0:1], 0x0
	s_add_u32 s30, s0, 0x98
	s_addc_u32 s31, s1, 0
	s_mov_b32 s88, s2
	s_waitcnt lgkmcnt(0)
	s_add_u32 s2, s6, 0x3eb60000
	v_writelane_b32 v254, s8, 0
	s_load_dword s89, s[0:1], 0x98
	v_and_b32_e32 v200, 0x3ff, v0
	v_writelane_b32 v254, s9, 1
	v_writelane_b32 v254, s10, 2
	v_writelane_b32 v254, s11, 3
	v_writelane_b32 v254, s12, 4
	v_writelane_b32 v254, s13, 5
	v_writelane_b32 v254, s14, 6
	v_writelane_b32 v254, s15, 7
	v_writelane_b32 v254, s16, 8
	v_writelane_b32 v254, s17, 9
	v_writelane_b32 v254, s18, 10
	v_writelane_b32 v254, s19, 11
	v_writelane_b32 v254, s20, 12
	v_writelane_b32 v254, s21, 13
	v_writelane_b32 v254, s22, 14
	v_writelane_b32 v254, s23, 15
	v_writelane_b32 v254, s4, 16
	s_addc_u32 s3, s7, 0
	v_or_b32_e32 v1, s88, v200
	v_writelane_b32 v254, s5, 17
	v_writelane_b32 v254, s6, 18
	v_writelane_b32 v254, s7, 19
	v_writelane_b32 v254, s2, 20
	v_cmp_eq_u32_e32 vcc, 0, v1
	s_nop 0
	v_writelane_b32 v254, s3, 21
	s_and_saveexec_b64 s[4:5], vcc
	s_cbranch_execz .LBB0_2
	v_readlane_b32 s2, v254, 20
	v_mov_b32_e32 v1, 0
	v_readlane_b32 s3, v254, 21
	s_nop 4
	global_store_dword v1, v1, s[2:3] sc1
	global_store_dword v1, v1, s[2:3] offset:64 sc1
	s_waitcnt vmcnt(0)
	v_mov_b32_e32 v2, 0x5a17c0de
	global_store_dword v1, v2, s[2:3] offset:128 sc1

; __device__ __forceinline__ void grid_bar(unsigned* ctr, unsigned target) {
;   __syncthreads();
;   if (threadIdx.x == 0) {
;     __builtin_amdgcn_fence(__ATOMIC_RELEASE, "agent");
;     asm volatile("s_waitcnt vmcnt(0)" ::: "memory");
;     __hip_atomic_fetch_add(ctr, 1u, __ATOMIC_RELAXED, __HIP_MEMORY_SCOPE_AGENT);
;     while (__hip_atomic_load(ctr, __ATOMIC_RELAXED, __HIP_MEMORY_SCOPE_AGENT) < target) __builtin_amdgcn_s_sleep(2);
;     __builtin_amdgcn_fence(__ATOMIC_ACQUIRE, "agent");
;     asm volatile("s_waitcnt vmcnt(0)" ::: "memory");
;   }
;   __syncthreads();
; __global__ void __launch_bounds__(512, 2) fwd_mega(Params p) {
;     ...
;   grid.sync();
;   REPS(1) {
;     g8::Sched S; S.init(16, 8, nb, (bid + (nb >> 1)) % nb); S.A0 = (const char*)(ws + OFF_WG); S.sAm = (size_t)256 * 1024 * 2; S.B0 = (const char*)(ws + OFF_WU); S.sBn = (size_t)256 * 1024 * 2; S.sBg = (size_t)2048 * 1024 * 2; S.gshift = 2;
.LBB0_362:
	s_or_b64 exec, exec, s[4:5]
	v_lshrrev_b32_e32 v1, 20, v0
	v_lshrrev_b32_e32 v0, 10, v0
	v_or_b32_e32 v0, v0, v1
	s_movk_i32 s2, 0x3ff
	v_and_or_b32 v0, v0, s2, v200
	v_cmp_eq_u32_e32 vcc, 0, v0
	s_barrier
	s_barrier
	s_and_saveexec_b64 s[4:5], vcc
	s_cbranch_execz .LBB0_372
	buffer_wbl2 sc1
	s_waitcnt vmcnt(0)
	v_readlane_b32 s6, v254, 20
	v_readlane_b32 s7, v254, 21
	v_mov_b32_e32 v0, 0
	s_mov_b32 s8, 0x5a17c0de
	s_nop 4
.Lgs_go:
	global_load_dword v1, v0, s[6:7] offset:128 sc1
	s_waitcnt vmcnt(0)
	v_cmp_eq_u32_e32 vcc, s8, v1
	s_cbranch_vccnz .Lgs_arrive
	s_sleep 2
	s_branch .Lgs_go
.Lgs_arrive:
	v_mov_b32_e32 v1, 1
	global_atomic_add v0, v1, s[6:7] offset:64
.Lgs_poll:
	global_load_dword v1, v0, s[6:7] offset:64 sc1
	s_waitcnt vmcnt(0)
	v_cmp_le_u32_e32 vcc, s89, v1
	s_cbranch_vccnz .Lgs_done
	s_sleep 2
	s_branch .Lgs_poll
.Lgs_done:
	buffer_inv sc1
	s_waitcnt vmcnt(0)
.LBB0_372:
	s_or_b64 exec, exec, s[4:5]
	s_abs_i32 s6, s89
	v_cvt_f32_u32_e32 v0, s6
	s_sub_i32 s3, 0, s6
	s_ashr_i32 s2, s89, 1
	s_add_i32 s2, s2, s88
	v_rcp_iflag_f32_e32 v1, v0
	s_ashr_i32 s4, s2, 31
	s_abs_i32 s2, s2
	v_mov_b32_e32 v0, v200
	v_mul_f32_e32 v1, 0x4f7ffffe, v1
	v_cvt_u32_f32_e32 v1, v1
	s_barrier
	v_readfirstlane_b32 s5, v1
	s_mul_i32 s3, s3, s5
	s_mul_hi_u32 s3, s5, s3
	s_add_i32 s3, s5, s3
	v_writelane_b32 v254, s3, 32
	s_mul_hi_u32 s3, s2, s3
	s_mul_i32 s3, s3, s6
	s_sub_i32 s2, s2, s3
	s_sub_i32 s3, s2, s6
	s_cmp_ge_u32 s2, s6
	s_cselect_b32 s2, s3, s2
	s_sub_i32 s3, s2, s6
	s_cmp_ge_u32 s2, s6
	s_cselect_b32 s2, s3, s2
	v_writelane_b32 v254, s6, 33
	s_xor_b32 s2, s2, s4
	s_sub_i32 s2, s2, s4
	v_readlane_b32 s4, v254, 16
	v_readlane_b32 s6, v254, 18
	v_readlane_b32 s7, v254, 19
	s_add_u32 s3, s6, 0x31000000
	v_readlane_b32 s5, v254, 17
	v_writelane_b32 v254, s3, 34
	s_addc_u32 s3, s7, 0
	v_writelane_b32 v254, s3, 35
	s_cmpk_gt_i32 s2, 0x7f
	v_readfirstlane_b32 s7, v0
	s_cbranch_scc1 .LBB0_396
	s_ashr_i32 s3, s2, 31
	s_lshr_b32 s3, s3, 29
	s_add_i32 s8, s2, s3
	s_and_b32 s3, s8, -8
	s_sub_i32 s3, s2, s3
	s_cmp_gt_i32 s3, -1
	s_cbranch_scc0 .LBB0_375
	s_lshl_b32 s6, s3, 4
	s_ashr_i32 s4, s8, 3
	s_cbranch_execz .LBB0_376
	s_branch .LBB0_377

; __global__ void __launch_bounds__(512, 2) fwd_mega(Params p) {
;     ...
;   if (bid == 0 && threadIdx.x == 0) __hip_atomic_store(bar, 0u, __ATOMIC_RELAXED, __HIP_MEMORY_SCOPE_AGENT);
;   REPS(0) { p0_prep(p, lds, bid, nb); __syncthreads(); }
;   grid.sync();
.LBB0_1248:
	s_mov_b64 exec, -1
	v_or_b32_e32 v0, s88, v200
	v_cmp_eq_u32_e32 vcc, 0, v0
	s_and_saveexec_b64 s[0:1], vcc
	s_cbranch_execz .Lgs_end
	v_readlane_b32 s2, v254, 20
	v_readlane_b32 s3, v254, 21
	v_mov_b32_e32 v0, 0
	s_nop 4
	global_store_dword v0, v0, s[2:3] offset:128 sc1
